# P2 tail: carry-row copy-out loops done by workgroups 128..255 beside the sample-row pooling loop on workgroups 0..127
# speedup vs baseline: 1.0029x; 1.0029x over previous
; DEV float bf2f(unsigned b) { return __uint_as_float(b << 16); }
; __global__ void __launch_bounds__(512) hymba_fwd(Params p) {
;     ...
;         for (int i = bid * 512 + tid; i < NB * (3 * 3072 + 15 * 1024); i += G * 512) {
;             const int b = i / (3 * 3072 + 15 * 1024), u = i - b * (3 * 3072 + 15 * 1024);
;             if (u < 3 * 3072) { const int rr = u / 3072, col = u - rr * 3072; p.out[O_CP + ((size_t)(b * 3 + rr)) * 3072 + col] = bf2f(proj[(size_t)(b * SEQ + 2045 + rr) * NPJ + col]); }
;             else { const int v = u - 3 * 3072, rr = v >> 10, col = v & 1023; p.out[O_PP + ((size_t)(b * 15 + rr)) * 1024 + col] = bf2f(proj[(size_t)(b * SEQ + 2033 + rr) * NPJ + C_U + col]); }
;         }
.LBB0_755:
	s_or_b64 exec, exec, s[4:5]
	s_mov_b32 s96, s2
	s_mov_b32 s97, s33
	s_cmpk_lg_i32 s33, 0x100
	s_cbranch_scc1 .Lp2t_done
	s_movk_i32 s97, 0x80
	s_sub_i32 s96, s2, 0x80
	s_cmp_ge_i32 s96, 0
	s_cbranch_scc1 .Lp2t_hi
	v_mov_b32_e32 v136, 0x7fffffff
	s_branch .Lp2t_done
.Lp2t_hi:
	v_add_u32_e32 v136, 0xffff0000, v136
.Lp2t_done:
	s_mov_b32 s4, 0x18000
	v_cmp_gt_i32_e32 vcc, s4, v136
	s_and_saveexec_b64 s[4:5], vcc
	s_cbranch_execz .LBB0_762
	s_load_dwordx2 s[6:7], s[0:1], 0xc0
	s_lshl_b32 s16, s97, 9
	s_mov_b64 s[8:9], 0
	s_mov_b32 s17, 0x2aaaaaab
	s_movk_i32 s18, 0xa000
	s_movk_i32 s19, 0x23ff
	s_movk_i32 s20, 0x7f1
	v_mov_b32_e32 v3, 0
	s_movk_i32 s21, 0x3000
	s_mov_b64 s[10:11], 0x2000
	s_movk_i32 s22, 0x7fd
	s_mov_b32 s23, 0x17fff
	v_mov_b32_e32 v12, v136
	s_branch .LBB0_758

; __global__ void __launch_bounds__(512) hymba_fwd(Params p) {
;     ...
;         for (int i = bid * 512 + tid; i < SB * 11 * 256; i += G * 512) {
;             const int c4 = (i & 255) * 4, rr = (i >> 8) % 11, sb = (i >> 8) / 11;
;             *(f32x4*)(p.out + O_PS + ((size_t)sb * 15 + rr) * 1024 + c4) = *(const f32x4*)(p.in[7] + ((size_t)sb * 15 + rr + 4) * 1024 + c4);
;         }
.LBB0_762:
	s_or_b64 exec, exec, s[4:5]
	s_mov_b32 s4, 0x58000
	v_cmp_gt_i32_e32 vcc, s4, v136
	s_and_saveexec_b64 s[4:5], vcc
	s_cbranch_execz .LBB0_765
	s_load_dwordx2 s[8:9], s[0:1], 0xc0
	s_load_dwordx2 s[6:7], s[0:1], 0x38
	v_lshlrev_b32_e32 v1, 2, v1
	v_lshl_add_u32 v1, s96, 11, v1
	s_mov_b64 s[10:11], 0
	s_waitcnt lgkmcnt(0)
	s_add_u32 s8, s8, 0x9ae0000
	s_addc_u32 s9, s9, 0
	s_lshl_b32 s12, s97, 9
	s_lshl_b32 s13, s97, 11
	s_mov_b32 s16, 0x2e8ba2e9
	v_mov_b32_e32 v3, 0
	s_mov_b32 s17, 0x57fff
